# v42 + scan L2 warmers: the per-step warm loads are issued back to back instead of one drained load at a time (GDN and GLA warmers keep their lead)
# speedup vs baseline: 1.0025x; 1.0025x over previous
; __device__ __forceinline__ void gdn_warm_wg(const Ctx& F, int hv, int wi) {
;     ...
;         while (true) { const int p = __hip_atomic_load(prog, __ATOMIC_RELAXED, __HIP_MEMORY_SCOPE_AGENT); if (p + 12 >= n || ++spins > 4000) break; __builtin_amdgcn_s_sleep(16); }
;         const size_t u = (size_t)hv * 256 + n;
; #pragma unroll
;         for (int i = 0; i < 3; ++i) { const int li = wi * 192 + i * 64 + F.lane;
;             const char* a = (li < 256) ? (Pg + u * 32768 + (size_t)li * 128) : (li < 512) ? (RTg + u * 32768 + (size_t)(li - 256) * 128) : (li < 640) ? (QEg + u * 16384 + (size_t)(li - 512) * 128) : (OUg + u * 16384 + (size_t)(li - 640) * 128);
;             sum += *(const volatile unsigned*)a; }
.LBB0_884:
	s_add_i32 s14, s28, s27
	s_lshl_b64 s[18:19], s[14:15], 14
	s_add_u32 s29, s25, s18
	s_addc_u32 s30, s26, s19
	s_add_u32 s31, s23, s18
	s_addc_u32 s34, s24, s19
	s_lshl_b64 s[18:19], s[14:15], 15
	s_add_u32 s14, s21, s18
	s_addc_u32 s35, s22, s19
	s_add_u32 s40, s3, s18
	s_addc_u32 s41, s20, s19
	s_and_b64 s[18:19], s[4:5], exec
	s_cselect_b32 s44, s40, s14
	s_cselect_b32 s45, s41, s35
	s_and_b64 s[18:19], s[16:17], exec
	s_cselect_b32 s52, s31, s29
	s_cselect_b32 s53, s34, s30
	s_and_b64 s[18:19], s[0:1], exec
	s_cselect_b32 s19, s45, s53
	s_cselect_b32 s18, s44, s52
	v_lshl_add_u64 v[8:9], s[18:19], 0, v[2:3]
	flat_load_dword v13, v[8:9] sc0 sc1
	s_cselect_b32 s19, s35, s30
	s_cselect_b32 s18, s14, s29
	v_mov_b32_e32 v10, s41
	v_mov_b32_e32 v11, s40
	s_cselect_b32 s30, s34, s30
	s_cselect_b32 s29, s31, s29
	v_mov_b32_e32 v8, s19
	v_cndmask_b32_e64 v9, v8, v10, s[6:7]
	v_mov_b32_e32 v8, s18
	v_cndmask_b32_e64 v8, v8, v11, s[6:7]
	s_and_b64 s[18:19], s[4:5], exec
	v_lshl_add_u64 v[8:9], v[8:9], 0, v[4:5]
	s_cselect_b32 s18, s35, s30
	flat_load_dword v12, v[8:9] sc0 sc1
	s_cselect_b32 s14, s14, s29
	v_mov_b32_e32 v8, s18
	v_cndmask_b32_e64 v9, v8, v10, s[8:9]
	v_mov_b32_e32 v8, s14
	v_cndmask_b32_e64 v8, v8, v11, s[8:9]
	v_lshl_add_u64 v[8:9], v[8:9], 0, v[6:7]
	flat_load_dword v14, v[8:9] sc0 sc1
	s_waitcnt vmcnt(0)
	s_add_i32 s14, s28, 8
	s_cmpk_gt_u32 s28, 0xf7
	s_waitcnt lgkmcnt(0)
	v_add3_u32 v0, v0, v12, v14
	v_add_u32_e32 v0, v13, v0
	s_cbranch_scc1 .LBB0_886
	s_mov_b32 s28, s14
	s_branch .LBB0_878

; __device__ __forceinline__ void gla_warm_wg(const Ctx& F, int xcd, int wi) {
;     ...
;         const size_t u = (size_t)h * 256 + n;
; #pragma unroll
;         for (int i = 0; i < 5; ++i) { const int li = wi * 272 + i * 64 + F.lane;
;             if (i * 64 + F.lane < 272) {
;                 const char* a = (li < 256) ? (QT + u * 32768 + (size_t)li * 128) : (li < 512) ? (KDTb + u * 32768 + (size_t)(li - 256) * 128) : (li < 576) ? (ATTb + u * 8192 + (size_t)(li - 512) * 128) : (VTb + u * 65536 + (size_t)(li - 576) * 128);
;                 sum += *(const volatile unsigned*)a; } }
.LBB0_1710:
	s_add_i32 s40, s54, s53
	s_lshl_b64 s[44:45], s[40:41], 16
	s_add_u32 s56, s51, s44
	s_addc_u32 s55, s52, s45
	s_lshl_b64 s[44:45], s[40:41], 13
	s_add_u32 s58, s49, s44
	s_addc_u32 s57, s50, s45
	s_lshl_b64 s[44:45], s[40:41], 15
	s_add_u32 s60, s47, s44
	s_addc_u32 s40, s48, s45
	s_add_u32 s61, s3, s44
	s_addc_u32 s59, s46, s45
	v_mov_b32_e32 v14, s60
	v_mov_b32_e32 v15, s61
	v_mov_b32_e32 v16, s40
	v_mov_b32_e32 v17, s59
	v_mov_b32_e32 v18, s56
	v_mov_b32_e32 v19, s58
	v_mov_b32_e32 v21, s55
	v_mov_b32_e32 v22, s57
	v_cndmask_b32_e64 v12, v14, v15, s[4:5]
	v_cndmask_b32_e64 v13, v16, v17, s[4:5]
	v_cndmask_b32_e64 v20, v18, v19, s[6:7]
	v_cndmask_b32_e64 v23, v21, v22, s[6:7]
	v_cndmask_b32_e64 v13, v23, v13, s[8:9]
	v_cndmask_b32_e64 v12, v20, v12, s[8:9]
	v_lshl_add_u64 v[12:13], v[12:13], 0, v[0:1]
	flat_load_dword v20, v[12:13] sc0 sc1
	v_cndmask_b32_e64 v12, v14, v15, s[10:11]
	v_cndmask_b32_e64 v13, v16, v17, s[10:11]
	v_cndmask_b32_e64 v23, v18, v19, s[12:13]
	v_cndmask_b32_e64 v24, v21, v22, s[12:13]
	v_cndmask_b32_e64 v13, v24, v13, s[14:15]
	v_cndmask_b32_e64 v12, v23, v12, s[14:15]
	v_lshl_add_u64 v[12:13], v[12:13], 0, v[2:3]
	flat_load_dword v23, v[12:13] sc0 sc1
	v_cndmask_b32_e64 v12, v14, v15, s[16:17]
	v_cndmask_b32_e64 v13, v16, v17, s[16:17]
	v_cndmask_b32_e64 v24, v18, v19, s[18:19]
	v_cndmask_b32_e64 v25, v21, v22, s[18:19]
	v_cndmask_b32_e64 v13, v25, v13, s[20:21]
	v_cndmask_b32_e64 v12, v24, v12, s[20:21]
	v_lshl_add_u64 v[12:13], v[12:13], 0, v[4:5]
	flat_load_dword v24, v[12:13] sc0 sc1
	v_cndmask_b32_e64 v12, v14, v15, s[22:23]
	v_cndmask_b32_e64 v13, v16, v17, s[22:23]
	v_cndmask_b32_e64 v14, v18, v19, s[24:25]
	v_cndmask_b32_e64 v15, v21, v22, s[24:25]
	v_cndmask_b32_e64 v13, v15, v13, s[26:27]
	v_cndmask_b32_e64 v12, v14, v12, s[26:27]
	v_lshl_add_u64 v[12:13], v[12:13], 0, v[6:7]
	flat_load_dword v12, v[12:13] sc0 sc1
	s_waitcnt vmcnt(0) lgkmcnt(0)
	v_add3_u32 v11, v20, v11, v23
	v_add3_u32 v11, v11, v24, v12
	s_and_saveexec_b64 s[44:45], s[0:1]
	s_cbranch_execz .LBB0_1712
	v_mov_b32_e32 v12, s60
	v_mov_b32_e32 v13, s61
	v_cndmask_b32_e64 v12, v12, v13, s[28:29]
	v_mov_b32_e32 v13, s40
	v_mov_b32_e32 v14, s59
	v_cndmask_b32_e64 v13, v13, v14, s[28:29]
	v_mov_b32_e32 v14, s56
	v_mov_b32_e32 v15, s58
	v_cndmask_b32_e64 v14, v14, v15, s[30:31]
	v_mov_b32_e32 v15, s55
	v_mov_b32_e32 v16, s57
	v_cndmask_b32_e64 v15, v15, v16, s[30:31]
	v_cndmask_b32_e64 v13, v15, v13, s[34:35]
	v_cndmask_b32_e64 v12, v14, v12, s[34:35]
	v_lshl_add_u64 v[12:13], v[12:13], 0, v[8:9]
	flat_load_dword v12, v[12:13] sc0 sc1
	s_waitcnt vmcnt(0) lgkmcnt(0)
	v_add_u32_e32 v11, v12, v11
